# q/kv projection items: redundant second entry barrier removed
# baseline (speedup 1.0000x reference)
; template <int WN, int WT>
; DEV void gemm_mainloop(const u16* __restrict__ Wt, long ldw, const u16* __restrict__ A, long lda, int K,
;                        char* smem, int tid, f32x4 (&acc)[WN][WT]) {
;     ...
;   __syncthreads();
;   stage_tile<NR>(Wt, ldw, 0, smem, tid);
;   stage_tile<TR>(A, lda, 0, smem + WB, tid);
;   if (nk > 1) {
;     stage_tile<NR>(Wt, ldw, 64, smem + STG, tid);
;     stage_tile<TR>(A, lda, 64, smem + STG + WB, tid);
;   }
; DEV void kvproj_item(const Params& p, int l, int tt, int tf, char* smem, int tid) {
;   const int t0 = tt * 192, f0 = tf * 128;
;   f32x4 acc[2][6];
;   zero_acc<2, 6>(acc);
;   float* rs = (float*)(smem + 122880);
;   __syncthreads();
;   row_scales(p.z + (long)t0 * NINP, C_CKV, 128, rs, tid);
;   gemm_mainloop<2, 6>(p.WukvT + ((long)l * 1024 + f0) * 128, 128, p.z + (long)t0 * NINP + C_CKV, NINP, 128, smem, tid, acc);
.LBB0_755:
	s_and_b64 vcc, exec, s[6:7]
	s_cbranch_vccz .LBB0_765
	s_add_i32 s6, s15, 0xffb8
	s_and_b32 s7, s6, 0xff
	s_and_b32 s11, s7, 7
	s_lshr_b32 s6, s7, 3
	v_readlane_b32 s7, v255, 10
	s_add_i32 s10, s7, s6
	s_mul_i32 s6, s10, 0x330000
	s_add_u32 s6, s88, s6
	s_movk_i32 s8, 0x180
	s_addc_u32 s7, s89, 0
	v_cmp_gt_i32_e32 vcc, s8, v58
	s_barrier
	s_mov_b32 s100, s6
	s_mov_b32 s101, s7
	v_ashrrev_i32_e32 v2, 3, v58
	s_and_b32 s11, 0xffff, s11
	s_waitcnt lgkmcnt(0)
	v_lshrrev_b32_e32 v12, 4, v58
	v_ashrrev_i32_e32 v3, 31, v2
	s_lshl_b32 s8, s11, 15
	v_xor_b32_e32 v0, v12, v58
	v_lshlrev_b64 v[4:5], 8, v[2:3]
	v_add_u32_e32 v3, 0x200, v58
	s_add_u32 s8, s12, s8
	v_lshlrev_b32_e32 v0, 4, v0
	v_ashrrev_i32_e32 v6, 3, v3
	s_addc_u32 s9, s13, 0
	v_and_b32_e32 v156, 0x70, v0
	v_ashrrev_i32_e32 v7, 31, v6
	s_waitcnt lgkmcnt(0)
	v_lshl_add_u64 v[0:1], s[8:9], 0, v[156:157]
	v_lshlrev_b32_e32 v13, 4, v58
	v_lshlrev_b64 v[8:9], 8, v[6:7]
	v_lshl_add_u64 v[4:5], v[0:1], 0, v[4:5]
	v_readfirstlane_b32 s8, v13
	v_lshl_add_u64 v[0:1], v[0:1], 0, v[8:9]
	v_lshlrev_b32_e32 v14, 4, v3
	v_lshl_add_u64 v[8:9], s[6:7], 0, v[156:157]
	s_mov_b32 m0, s8
	v_readfirstlane_b32 s8, v14
	v_mad_i64_i32 v[2:3], s[6:7], v2, s33, v[8:9]
	v_add_u32_e32 v7, 0x4000, v13
	s_nop 0
	global_load_lds_dwordx4 v[4:5], off
	s_mov_b32 m0, s8
	v_readfirstlane_b32 s6, v7
	global_load_lds_dwordx4 v[0:1], off
	s_mov_b64 s[8:9], 0x200
	s_mov_b32 m0, s6
	v_mad_i64_i32 v[6:7], s[6:7], v6, s33, v[8:9]
	v_add_u32_e32 v15, 0x4000, v14
	v_lshl_add_u64 v[10:11], v[2:3], 0, s[8:9]
	v_readfirstlane_b32 s6, v15
	global_load_lds_dwordx4 v[10:11], off
	v_lshl_add_u64 v[10:11], v[6:7], 0, s[8:9]
	s_mov_b32 m0, s6
	v_add_u32_e32 v15, 0x400, v58
	global_load_lds_dwordx4 v[10:11], off
	v_ashrrev_i32_e32 v10, 3, v15
	v_lshlrev_b32_e32 v15, 4, v15
	v_mad_i64_i32 v[8:9], s[6:7], v10, s33, v[8:9]
	v_add_u32_e32 v16, 0x4000, v15
	v_lshl_add_u64 v[10:11], v[8:9], 0, s[8:9]
	v_readfirstlane_b32 s6, v16
	s_mov_b32 m0, s6
	v_lshl_add_u64 v[4:5], v[4:5], 0, s[34:35]
	global_load_lds_dwordx4 v[10:11], off
	v_add_u32_e32 v10, 0xa000, v13
	v_lshl_add_u64 v[0:1], v[0:1], 0, s[34:35]
	v_readfirstlane_b32 s6, v10
	s_mov_b32 m0, s6
	s_mov_b64 s[8:9], 0x280
	global_load_lds_dwordx4 v[4:5], off
	v_add_u32_e32 v4, 0xa000, v14
	s_mov_b32 s16, 0
	v_readfirstlane_b32 s6, v4
	s_mov_b32 m0, s6
	v_bfe_u32 v4, v58, 1, 3
	global_load_lds_dwordx4 v[0:1], off
	v_lshl_add_u64 v[0:1], v[2:3], 0, s[8:9]
	v_add_u32_e32 v2, 0xe000, v13
	v_lshrrev_b32_e32 v3, 1, v58
	v_readfirstlane_b32 s6, v2
	v_add_u32_e32 v2, 0xe000, v14
	s_mov_b32 m0, s6
	v_readfirstlane_b32 s6, v2
	v_add_u32_e32 v2, 0xe000, v15
	global_load_lds_dwordx4 v[0:1], off
	v_lshl_add_u64 v[0:1], v[6:7], 0, s[8:9]
	s_mov_b32 m0, s6
	v_readfirstlane_b32 s6, v2
	global_load_lds_dwordx4 v[0:1], off
	v_lshl_add_u64 v[0:1], v[8:9], 0, s[8:9]
	s_mov_b32 m0, s6
	v_and_b32_e32 v2, 15, v58
	global_load_lds_dwordx4 v[0:1], off
	s_mov_b32 s6, s100
	s_mov_b32 s7, s101
	s_mov_b32 s98, s16
	v_mov_b32_e32 v133, v2
	v_mov_b32_e32 v134, v3
	v_mov_b32_e32 v135, v4
	v_mov_b32_e32 v136, v12
	s_and_saveexec_b64 s[8:9], vcc
	s_cbranch_execz .LBB0_759
; DEV float bflo(unsigned w) { return __uint_as_float(w << 16); }
; DEV float bfhi(unsigned w) { return __uint_as_float(w & 0xffff0000u); }
; DEV void row_scales(const u16* __restrict__ zrow0, int col0, int ncol, float* rs, int tid) {
;   if (tid >= 384) return;
;   const int r = tid >> 1, h = tid & 1, lane = tid & 63;
;   const u16* s = zrow0 + (long)r * NINP + col0 + h * (ncol / 2);
;   float ss = 0.f;
;   for (int i = 0; i < ncol / 2; i += 8) {
;     uint4 v = *(const uint4*)(s + i);
;     ss += bflo(v.x) * bflo(v.x) + bfhi(v.x) * bfhi(v.x) + bflo(v.y) * bflo(v.y) + bfhi(v.y) * bfhi(v.y) +
;           bflo(v.z) * bflo(v.z) + bfhi(v.z) * bfhi(v.z) + bflo(v.w) * bflo(v.w) + bfhi(v.w) * bfhi(v.w);
;   }
;   ss += shx(ss, 1, lane);
;   if (h == 0) rs[r] = rsqrtf(ss / (float)ncol + 1e-6f);
; }
	v_ashrrev_i32_e32 v16, 1, v58
	v_and_b32_e32 v17, 1, v58
	v_mov_b64_e32 v[0:1], s[6:7]
	v_mad_i64_i32 v[0:1], s[16:17], v16, s33, v[0:1]
	v_lshlrev_b32_e32 v156, 7, v17
	s_waitcnt lgkmcnt(0)
	v_lshl_add_u64 v[12:13], v[0:1], 0, v[156:157]
	global_load_dwordx4 v[0:3], v[12:13], off offset:560
	global_load_dwordx4 v[4:7], v[12:13], off offset:544
	global_load_dwordx4 v[8:11], v[12:13], off offset:528
	global_load_dwordx4 v[18:21], v[12:13], off offset:512
	global_load_dwordx4 v[100:103], v[12:13], off offset:624
	global_load_dwordx4 v[104:107], v[12:13], off offset:608
	global_load_dwordx4 v[108:111], v[12:13], off offset:592
	global_load_dwordx4 v[112:115], v[12:13], off offset:576
	v_cmp_eq_u32_e32 vcc, 0, v17
	s_waitcnt vmcnt(4)
	v_and_b32_e32 v15, 0xffff0000, v18
	v_lshlrev_b32_e32 v14, 16, v18
	v_mul_f32_e32 v15, v15, v15
	v_fmac_f32_e32 v15, v14, v14
	v_lshlrev_b32_e32 v14, 16, v19
	v_fmac_f32_e32 v15, v14, v14
	v_and_b32_e32 v14, 0xffff0000, v19
	v_fmac_f32_e32 v15, v14, v14
	v_lshlrev_b32_e32 v14, 16, v20
	v_fmac_f32_e32 v15, v14, v14
	v_and_b32_e32 v14, 0xffff0000, v20
	v_fmac_f32_e32 v15, v14, v14
	v_lshlrev_b32_e32 v14, 16, v21
	v_fmac_f32_e32 v15, v14, v14
	v_and_b32_e32 v14, 0xffff0000, v21
	v_fmac_f32_e32 v15, v14, v14
	v_lshlrev_b32_e32 v14, 16, v8
	v_and_b32_e32 v8, 0xffff0000, v8
	v_mul_f32_e32 v8, v8, v8
	v_fmac_f32_e32 v8, v14, v14
	v_lshlrev_b32_e32 v14, 16, v9
	v_fmac_f32_e32 v8, v14, v14
	v_and_b32_e32 v9, 0xffff0000, v9
	v_fmac_f32_e32 v8, v9, v9
	v_lshlrev_b32_e32 v9, 16, v10
	v_fmac_f32_e32 v8, v9, v9
	v_and_b32_e32 v9, 0xffff0000, v10
	v_fmac_f32_e32 v8, v9, v9
	v_lshlrev_b32_e32 v9, 16, v11
	v_fmac_f32_e32 v8, v9, v9
	v_and_b32_e32 v9, 0xffff0000, v11
	v_fmac_f32_e32 v8, v9, v9
	v_lshlrev_b32_e32 v9, 16, v4
	v_and_b32_e32 v4, 0xffff0000, v4
	v_mul_f32_e32 v4, v4, v4
	v_fmac_f32_e32 v4, v9, v9
	v_lshlrev_b32_e32 v9, 16, v5
	v_fmac_f32_e32 v4, v9, v9
	v_and_b32_e32 v5, 0xffff0000, v5
	v_fmac_f32_e32 v4, v5, v5
	v_lshlrev_b32_e32 v5, 16, v6
	v_fmac_f32_e32 v4, v5, v5
	v_and_b32_e32 v5, 0xffff0000, v6
	v_fmac_f32_e32 v4, v5, v5
	v_lshlrev_b32_e32 v5, 16, v7
	v_fmac_f32_e32 v4, v5, v5
	v_and_b32_e32 v5, 0xffff0000, v7
	v_fmac_f32_e32 v4, v5, v5
	v_lshlrev_b32_e32 v5, 16, v0
	v_and_b32_e32 v0, 0xffff0000, v0
	v_mul_f32_e32 v0, v0, v0
	v_fmac_f32_e32 v0, v5, v5
	v_lshlrev_b32_e32 v5, 16, v1
	v_fmac_f32_e32 v0, v5, v5
	v_and_b32_e32 v1, 0xffff0000, v1
	v_fmac_f32_e32 v0, v1, v1
	v_lshlrev_b32_e32 v1, 16, v2
	v_fmac_f32_e32 v0, v1, v1
	v_and_b32_e32 v1, 0xffff0000, v2
	v_fmac_f32_e32 v0, v1, v1
	v_lshlrev_b32_e32 v1, 16, v3
	v_add_f32_e32 v8, v15, v8
	v_fmac_f32_e32 v0, v1, v1
	v_and_b32_e32 v1, 0xffff0000, v3
	v_add_f32_e32 v4, v8, v4
	v_fmac_f32_e32 v0, v1, v1
	v_add_f32_e32 v18, v4, v0
	s_waitcnt vmcnt(0)
	v_lshlrev_b32_e32 v19, 16, v112
	v_and_b32_e32 v112, 0xffff0000, v112
	v_mul_f32_e32 v112, v112, v112
	v_fmac_f32_e32 v112, v19, v19
	v_lshlrev_b32_e32 v19, 16, v113
	v_fmac_f32_e32 v112, v19, v19
	v_and_b32_e32 v113, 0xffff0000, v113
	v_fmac_f32_e32 v112, v113, v113
	v_lshlrev_b32_e32 v113, 16, v114
	v_fmac_f32_e32 v112, v113, v113
	v_and_b32_e32 v113, 0xffff0000, v114
	v_fmac_f32_e32 v112, v113, v113
	v_lshlrev_b32_e32 v113, 16, v115
	v_fmac_f32_e32 v112, v113, v113
	v_and_b32_e32 v113, 0xffff0000, v115
	v_fmac_f32_e32 v112, v113, v113
	v_lshlrev_b32_e32 v113, 16, v108
	v_and_b32_e32 v108, 0xffff0000, v108
	v_mul_f32_e32 v108, v108, v108
	v_fmac_f32_e32 v108, v113, v113
	v_lshlrev_b32_e32 v113, 16, v109
	v_fmac_f32_e32 v108, v113, v113
	v_and_b32_e32 v109, 0xffff0000, v109
	v_fmac_f32_e32 v108, v109, v109
	v_lshlrev_b32_e32 v109, 16, v110
	v_fmac_f32_e32 v108, v109, v109
	v_and_b32_e32 v109, 0xffff0000, v110
	v_fmac_f32_e32 v108, v109, v109
	v_lshlrev_b32_e32 v109, 16, v111
	v_fmac_f32_e32 v108, v109, v109
	v_and_b32_e32 v109, 0xffff0000, v111
	v_fmac_f32_e32 v108, v109, v109
	v_lshlrev_b32_e32 v109, 16, v104
	v_and_b32_e32 v104, 0xffff0000, v104
	v_mul_f32_e32 v104, v104, v104
	v_fmac_f32_e32 v104, v109, v109
	v_lshlrev_b32_e32 v109, 16, v105
	v_fmac_f32_e32 v104, v109, v109
	v_and_b32_e32 v105, 0xffff0000, v105
	v_fmac_f32_e32 v104, v105, v105
	v_lshlrev_b32_e32 v105, 16, v106
	v_fmac_f32_e32 v104, v105, v105
	v_and_b32_e32 v105, 0xffff0000, v106
	v_fmac_f32_e32 v104, v105, v105
	v_lshlrev_b32_e32 v105, 16, v107
	v_fmac_f32_e32 v104, v105, v105
	v_and_b32_e32 v105, 0xffff0000, v107
	v_fmac_f32_e32 v104, v105, v105
	v_lshlrev_b32_e32 v105, 16, v100
	v_and_b32_e32 v100, 0xffff0000, v100
	v_mul_f32_e32 v100, v100, v100
	v_fmac_f32_e32 v100, v105, v105
	v_lshlrev_b32_e32 v105, 16, v101
	v_fmac_f32_e32 v100, v105, v105
	v_and_b32_e32 v101, 0xffff0000, v101
	v_fmac_f32_e32 v100, v101, v101
	v_lshlrev_b32_e32 v101, 16, v102
	v_fmac_f32_e32 v100, v101, v101
	v_and_b32_e32 v101, 0xffff0000, v102
	v_add_f32_e32 v112, v18, v112
	v_fmac_f32_e32 v100, v101, v101
	v_lshlrev_b32_e32 v101, 16, v103
	v_add_f32_e32 v108, v112, v108
	v_fmac_f32_e32 v100, v101, v101
	v_and_b32_e32 v101, 0xffff0000, v103
	v_add_f32_e32 v104, v108, v104
	v_fmac_f32_e32 v100, v101, v101
	v_lshlrev_b32_e32 v1, 2, v58
	v_add_f32_e32 v0, v104, v100
	v_bitop3_b32 v1, v1, 4, v252 bitop3:0x6c
	ds_bpermute_b32 v1, v1, v0
	s_and_b64 exec, exec, vcc
	s_cbranch_execz .LBB0_759
	s_waitcnt lgkmcnt(0)
	v_add_f32_e32 v0, v0, v1
	v_fmamk_f32 v0, v0, 0x3c000000, v196
	s_mov_b32 s16, 0x800000
	v_mul_f32_e32 v1, 0x4b800000, v0
	v_cmp_gt_f32_e32 vcc, s16, v0
	s_nop 1
	v_cndmask_b32_e32 v0, v0, v1, vcc
	v_rsq_f32_e32 v0, v0
	s_nop 0
	v_mul_f32_e32 v1, 0x45800000, v0
	v_cndmask_b32_e32 v0, v0, v1, vcc
	v_mov_b32_e32 v1, 0x1e000
	v_lshl_add_u32 v1, v16, 2, v1
	ds_write_b32 v1, v0

; template <int WN, int WT>
; DEV void gemm_mainloop(const u16* __restrict__ Wt, long ldw, const u16* __restrict__ A, long lda, int K,
;                        char* smem, int tid, f32x4 (&acc)[WN][WT]) {
;     ...
;   __syncthreads();
;   stage_tile<NR>(Wt, ldw, 0, smem, tid);
;   stage_tile<TR>(A, lda, 0, smem + WB, tid);
;   if (nk > 1) {
;     stage_tile<NR>(Wt, ldw, 64, smem + STG, tid);
;     stage_tile<TR>(A, lda, 64, smem + STG + WB, tid);
;   }
; DEV void qproj_item(const Params& p, int l, int tt, int tf, char* smem, int tid) {
;   const int t0 = tt * 192, f0 = tf * 128;
;   f32x4 acc[2][6];
;   zero_acc<2, 6>(acc);
;   float* rs = (float*)(smem + 122880);
;   __syncthreads();
;   row_scales(p.z + (long)t0 * NINP, C_CQ, 256, rs, tid);
;   gemm_mainloop<2, 6>(p.WuqT + ((long)l * 768 + f0) * 256, 256, p.z + (long)t0 * NINP + C_CQ, NINP, 256, smem, tid, acc);
.LBB0_767:
	s_mul_i32 s6, s15, 43
	s_lshr_b32 s16, s6, 8
	s_mul_i32 s6, s16, 6
	s_sub_i32 s10, s15, s6
	s_cmp_eq_u32 s16, 0
	v_readlane_b32 s8, v255, 42
	s_cselect_b64 s[6:7], -1, 0
	v_readlane_b32 s9, v255, 43
	s_and_b64 s[6:7], s[8:9], s[6:7]
	s_and_b64 vcc, exec, s[6:7]
	s_cbranch_vccnz .LBB0_749
	v_readlane_b32 s6, v255, 10
	s_add_i32 s16, s16, s6
	s_mul_i32 s17, s16, 0xc0
	s_movk_i32 s8, 0x180
	s_mul_i32 s6, s16, 0x330000
	s_mul_hi_i32 s7, s17, 0x4400
	v_cmp_gt_i32_e32 vcc, s8, v58
	s_waitcnt vmcnt(0)
	s_barrier
	v_and_b32_e32 v132, 0xff, v197
	v_lshlrev_b32_e32 v132, 4, v132
	global_load_dwordx4 v[128:131], v132, s[82:83]
	s_lshl_b32 s8, s10, 7
	s_add_u32 s10, s88, s6
	s_addc_u32 s11, s89, s7
	s_ashr_i32 s9, s8, 31
	s_mul_i32 s18, s14, 0x300
	s_add_u32 s18, s8, s18
	s_addc_u32 s19, s9, 0
	v_readlane_b32 s40, v253, 7
	v_lshrrev_b32_e32 v18, 4, v58
	v_ashrrev_i32_e32 v2, 3, v58
	s_lshl_b64 s[18:19], s[18:19], 9
	v_readlane_b32 s46, v253, 13
	s_waitcnt lgkmcnt(0)
	v_xor_b32_e32 v0, v18, v58
	v_ashrrev_i32_e32 v3, 31, v2
	v_readlane_b32 s47, v253, 14
	s_add_u32 s18, s46, s18
	v_lshlrev_b32_e32 v0, 4, v0
	v_lshlrev_b64 v[4:5], 9, v[2:3]
	v_add_u32_e32 v3, 0x200, v58
	s_addc_u32 s19, s47, s19
	v_and_b32_e32 v156, 0x70, v0
	v_lshlrev_b32_e32 v59, 4, v58
	v_ashrrev_i32_e32 v8, 3, v3
	v_lshl_add_u64 v[0:1], s[18:19], 0, v[156:157]
	v_readfirstlane_b32 s18, v59
	v_ashrrev_i32_e32 v9, 31, v8
	v_lshlrev_b32_e32 v60, 4, v3
	v_lshl_add_u64 v[12:13], s[10:11], 0, v[156:157]
	v_lshl_add_u64 v[6:7], v[0:1], 0, v[4:5]
	s_mov_b32 m0, s18
	v_lshlrev_b64 v[10:11], 9, v[8:9]
	v_readfirstlane_b32 s18, v60
	v_mad_i64_i32 v[14:15], s[10:11], v2, s33, v[12:13]
	v_add_u32_e32 v3, 0x4000, v59
	s_nop 0
	global_load_lds_dwordx4 v[6:7], off
	v_lshl_add_u64 v[0:1], v[0:1], 0, v[10:11]
	s_mov_b32 m0, s18
	v_readfirstlane_b32 s10, v3
	global_load_lds_dwordx4 v[0:1], off
	s_mov_b32 m0, s10
	v_mad_i64_i32 v[16:17], s[10:11], v8, s33, v[12:13]
	v_add_u32_e32 v3, 0x4000, v60
	global_load_lds_dwordx4 v[14:15], off
	v_readfirstlane_b32 s10, v3
	v_add_u32_e32 v3, 0x400, v58
	v_ashrrev_i32_e32 v9, 3, v3
	v_lshlrev_b32_e32 v61, 4, v3
	s_mov_b32 m0, s10
	v_mad_i64_i32 v[12:13], s[10:11], v9, s33, v[12:13]
	v_add_u32_e32 v3, 0x4000, v61
	global_load_lds_dwordx4 v[16:17], off
	v_readfirstlane_b32 s10, v3
	v_add_u32_e32 v3, 0xa000, v59
	s_mov_b32 m0, s10
	v_readfirstlane_b32 s10, v3
	v_add_u32_e32 v3, 0xa000, v60
	global_load_lds_dwordx4 v[12:13], off
	v_lshl_add_u64 v[6:7], v[6:7], 0, s[34:35]
	s_mov_b32 m0, s10
	v_readfirstlane_b32 s10, v3
	v_add_u32_e32 v3, 0xe000, v59
	global_load_lds_dwordx4 v[6:7], off
	v_lshl_add_u64 v[0:1], v[0:1], 0, s[34:35]
	s_mov_b32 m0, s10
	v_readfirstlane_b32 s10, v3
	v_add_u32_e32 v3, 0xe000, v60
	global_load_lds_dwordx4 v[0:1], off
	v_lshl_add_u64 v[0:1], v[14:15], 0, s[34:35]
	s_mov_b32 m0, s10
	v_readfirstlane_b32 s10, v3
	v_add_u32_e32 v3, 0xe000, v61
	global_load_lds_dwordx4 v[0:1], off
	v_lshl_add_u64 v[0:1], v[16:17], 0, s[34:35]
	s_mov_b32 m0, s10
	v_readfirstlane_b32 s10, v3
	global_load_lds_dwordx4 v[0:1], off
	v_lshl_add_u64 v[0:1], v[12:13], 0, s[34:35]
	s_mov_b32 m0, s10
	v_lshrrev_b32_e32 v63, 1, v58
	global_load_lds_dwordx4 v[0:1], off
	s_mov_b32 s98, s8
	s_mov_b32 s99, s9
	v_mov_b32_e32 v133, v2
	v_mov_b32_e32 v134, v4
	v_mov_b32_e32 v135, v5
	s_and_saveexec_b64 s[8:9], vcc
	s_cbranch_execz .LBB0_773
	v_ashrrev_i32_e32 v2, 1, v58
	v_mov_b64_e32 v[0:1], s[6:7]
	v_mad_i64_i32 v[0:1], s[18:19], v2, s33, v[0:1]
	v_and_b32_e32 v3, 1, v58
	v_lshlrev_b32_e32 v156, 8, v3
	v_readlane_b32 s18, v254, 37
	v_lshl_add_u64 v[0:1], v[0:1], 0, v[156:157]
	v_readlane_b32 s19, v254, 38
	v_mov_b32_e32 v4, 0
	s_mov_b32 s11, -8
	v_lshl_add_u64 v[0:1], s[18:19], 0, v[0:1]
